# GEMM tile order: 4 row tiles per column-major group instead of 8 (per XCD round 4 rows x 8 cols of tiles instead of 8 x 4)
# baseline (speedup 1.0000x reference)
;     __device__ bool next(int i, Unit& u) const {
;         const long L = (long)i * G + c; if (L >= nwg) return false;
;         int wgid = (int)L; { const int q = nwg / NXCD, r = nwg % NXCD, xcd = wgid % NXCD, off = wgid / NXCD; wgid = (xcd < r ? xcd * (q + 1) : r * (q + 1) + (xcd - r) * q) + off; }
;         const int nig = WGM * nN, gid = wgid / nig, fm = gid * WGM, gsz = (nM - fm) < WGM ? (nM - fm) : WGM;
;         u.pm = fm + ((wgid % nig) % gsz); u.pn = (wgid % nig) / gsz; return true;
;     }
.LBB0_254:
	s_lshl_b32 s4, s18, 2
	v_cvt_f32_u32_e32 v0, s4
	s_ashr_i32 s5, s8, 3
	s_sub_i32 s8, 0, s4
	s_add_i32 s5, s13, s5
	v_rcp_iflag_f32_e32 v0, v0
	s_abs_i32 s14, s5
	s_ashr_i32 s13, s5, 31
	v_mul_f32_e32 v0, 0x4f7ffffe, v0
	v_cvt_u32_f32_e32 v0, v0
	s_nop 0
	v_readfirstlane_b32 s15, v0
	s_mul_i32 s8, s8, s15
	s_mul_hi_u32 s8, s15, s8
	s_add_i32 s15, s15, s8
	s_mul_hi_u32 s8, s14, s15
	s_mul_i32 s15, s8, s4
	s_sub_i32 s14, s14, s15
	s_add_i32 s19, s8, 1
	s_sub_i32 s15, s14, s4
	s_cmp_ge_u32 s14, s4
	s_cselect_b32 s8, s19, s8
	s_cselect_b32 s14, s15, s14
	s_add_i32 s15, s8, 1
	s_cmp_ge_u32 s14, s4
	s_cselect_b32 s8, s15, s8
	s_xor_b32 s8, s8, s13
	s_sub_i32 s8, s8, s13
	s_lshl_b32 s13, s8, 2
	s_mul_i32 s8, s8, s4
	s_sub_i32 s4, s96, s13
	s_min_i32 s14, s4, 4
	s_sext_i32_i16 s4, s14
	v_cvt_f32_i32_e32 v0, s4
	s_sub_i32 s8, s5, s8
	s_sext_i32_i16 s5, s8
	v_cvt_f32_i32_e32 v2, s5
	v_rcp_iflag_f32_e32 v3, v0
	s_xor_b32 s4, s5, s4
	s_ashr_i32 s4, s4, 30
	s_or_b32 s15, s4, 1
	v_mul_f32_e32 v3, v2, v3
	v_trunc_f32_e32 v3, v3
	v_fma_f32 v2, -v3, v0, v2
	v_cvt_i32_f32_e32 v3, v3
	v_cmp_ge_f32_e64 s[4:5], |v2|, |v0|
	s_and_b64 s[4:5], s[4:5], exec
	s_cselect_b32 s4, s15, 0
	v_readfirstlane_b32 s5, v3
	s_add_i32 s4, s5, s4
	s_sext_i32_i16 s71, s4
	s_mul_i32 s4, s4, s14
	s_sub_i32 s4, s8, s4
	s_sext_i32_i16 s4, s4
	s_add_i32 s63, s13, s4

; __device__ __forceinline__ int opaque_tid(int wv) { int t = wv * 64 + (int)__builtin_amdgcn_mbcnt_hi(~0u, __builtin_amdgcn_mbcnt_lo(~0u, 0u)); asm volatile("" : "+v"(t)); return t; }
; #define PG8_STAGE(bufoff, gbase, voff) do { _Pragma("unroll") for (int _i = 0; _i < 2; ++_i) \
;         __builtin_amdgcn_global_load_lds((const unsigned*)((const char*)(gbase) + (voff)[_i]), (LAS unsigned*)(lds + (bufoff) + ldsw + _i * 8192), 16, 0, 0); } while (0)
; #define PG8_WAIT_V(n) asm volatile("s_waitcnt vmcnt(" #n ")" ::: "memory")
; #define PG8_BAR __builtin_amdgcn_s_barrier()
; template <class EpiT>
; __device__ __forceinline__ void gemm_phase(LAS unsigned char* lds, const Gemm g, const StaticOrder& S, const EpiT& E, int wv) {
;     const int tid = opaque_tid(wv), wid = __builtin_amdgcn_readfirstlane(tid >> 6), lane = tid & 63, wr = wid >> 2, wc = wid & 3, fr = lane & 15, fq = lane >> 4;
;     int K = g.K; asm volatile("" : "+s"(K)); const int nt = K / BK;
;     unsigned voffA[2], voffB[2];
; #pragma unroll
;     for (int i = 0; i < 2; ++i) { int R, C; stage_rc(tid * 16 + i * 8192, R, C); const int Rb = (R & ~31) + perm32(R & 31);
;         voffA[i] = (unsigned)(R * g.lda + C) * 2u; voffB[i] = (unsigned)(Rb * g.ldb + C) * 2u; }
;     const size_t kstep = (size_t)(BK * 2);
;     const size_t hA = (size_t)HALF * g.lda * 2, hB = (size_t)HALF * g.ldb * 2;
;     const size_t tA = 2 * hA, tB = 2 * hB;
;     const unsigned ldsw = (unsigned)wid * 1024u;
;     const int aoff = lds_byte(wr * 64 + fr, fq * 8), boff = lds_byte(wc * 32 + fr, fq * 8);
;     ...
;     const char* cA = (const char*)g.A + (size_t)cur.pm * tA + (size_t)cur.pn * g.apn * 2; const char* cB = (const char*)g.Bt + (size_t)cur.pn * tB;
;     PG8_STAGE(PG8_SB(0, 0), cB, voffB); PG8_STAGE(PG8_SB(0, 1), cB + hB, voffB); PG8_STAGE(PG8_SA(0, 0), cA, voffA); PG8_STAGE(PG8_SA(0, 1), cA + hA, voffA);
;     if (wr == 1) PG8_BAR;
;     PG8_WAIT_V(2); PG8_BAR;
;     PG8_STAGE(PG8_SB(1, 0), cB + kstep, voffB); PG8_STAGE(PG8_SA(1, 0), cA + kstep, voffA); PG8_STAGE(PG8_SB(1, 1), cB + hB + kstep, voffB);
;     PG8_WAIT_V(6); PG8_BAR;
.LBB0_258:
	s_add_i32 m0, s14, 0x18000
	v_lshl_add_u64 v[4:5], v[4:5], 0, s[10:11]
	s_waitcnt vmcnt(2)
	s_barrier
	global_load_lds_dwordx4 v[4:5], off
	v_lshl_add_u64 v[4:5], v[6:7], 0, s[10:11]
	s_add_i32 m0, s14, 0x1a000
	s_add_i32 s72, s14, 0x8000
	global_load_lds_dwordx4 v[4:5], off
	v_lshl_add_u64 v[4:5], v[12:13], 0, s[10:11]
	s_mov_b32 m0, s72
	s_add_i32 s73, s14, 0xa000
	global_load_lds_dwordx4 v[4:5], off
	v_lshl_add_u64 v[4:5], v[18:19], 0, s[10:11]
	s_mov_b32 m0, s73
	s_and_b32 s80, s0, 3
	global_load_lds_dwordx4 v[4:5], off
	s_add_i32 m0, s14, 0x1c000
	v_lshl_add_u64 v[4:5], v[8:9], 0, s[10:11]
	global_load_lds_dwordx4 v[4:5], off
	v_lshl_add_u64 v[4:5], v[10:11], 0, s[10:11]
	s_add_i32 m0, s14, 0x1e000
	s_ashr_i32 s0, s16, 31
	global_load_lds_dwordx4 v[4:5], off
	v_bfe_u32 v9, v20, 4, 2
	s_lshr_b32 s0, s0, 26
	v_and_b32_e32 v7, 15, v20
	s_add_i32 s0, s16, s0
	v_lshlrev_b32_e32 v6, 4, v9
	v_lshlrev_b32_e32 v8, 2, v20
	s_ashr_i32 s81, s0, 6
	v_lshl_or_b32 v17, s1, 6, v7
	v_lshl_or_b32 v7, v7, 6, v6
	s_lshl_b32 s0, s1, 13
	v_and_b32_e32 v8, 32, v8
	v_bitop3_b32 v12, v7, s0, v8 bitop3:0xde
	s_lshl_b32 s0, s80, 12
	s_cmp_gt_i32 s16, 63
	s_cselect_b64 s[68:69], -1, 0
	s_add_i32 s52, s81, -2
	s_cmpk_lt_u32 s17, 0x100
	s_cselect_b64 s[16:17], -1, 0
	s_lshl_b32 s57, s18, 2
	v_bitop3_b32 v234, v7, s0, v8 bitop3:0xde
	v_cvt_f32_u32_e32 v7, s57
	v_lshlrev_b32_e32 v0, 3, v9
	v_lshlrev_b32_e32 v8, 2, v9
	v_cmp_eq_u32_e64 s[82:83], 0, v9
	v_lshlrev_b32_e32 v10, 5, v9
	v_rcp_iflag_f32_e32 v9, v7
	s_lshr_b32 s0, s84, 3
	v_writelane_b32 v255, s0, 36
	s_add_i32 s99, s0, 1
	v_mul_f32_e32 v9, 0x4f7ffffe, v9
	v_cvt_u32_f32_e32 v9, v9
	v_readlane_b32 s0, v254, 50
	v_mov_b32_e32 v11, v1
	v_readlane_b32 s1, v254, 51
	v_mov_b32_e32 v7, v1
	s_waitcnt vmcnt(6)
	v_mov_b32_e32 v3, v2
	v_lshl_add_u64 v[188:189], s[0:1], 0, v[10:11]
	v_lshl_add_u64 v[190:191], s[0:1], 0, v[6:7]
	s_sub_i32 s0, 0, s57
	v_readfirstlane_b32 s1, v9
	s_mul_i32 s0, s0, s1
	s_mul_hi_u32 s0, s1, s0
	s_add_i32 s55, s1, s0
	v_readlane_b32 s0, v255, 22
	v_readlane_b32 s1, v255, 23
	v_mov_b32_e32 v4, v2
	v_mov_b32_e32 v5, v2
	v_lshl_add_u64 v[192:193], s[0:1], 0, v[0:1]
	v_readlane_b32 s0, v255, 24
	v_readlane_b32 s1, v255, 25
	v_or_b32_e32 v235, 16, v17
	v_or_b32_e32 v236, 32, v17
	v_lshl_add_u64 v[194:195], s[0:1], 0, v[6:7]
	v_add_u32_e32 v6, v23, v21
	v_add_lshl_u32 v6, v6, v22, 1
	v_lshl_add_u64 v[196:197], s[4:5], 0, v[6:7]
	v_add_u32_e32 v6, v26, v24
	v_add_lshl_u32 v6, v6, v25, 1
	v_or_b32_e32 v237, 48, v17
	v_add_u32_e32 v238, 0x90, v17
	v_add_u32_e32 v239, 0xa0, v17
	v_add_u32_e32 v240, 0xb0, v17
	s_mov_b32 s53, 0
	s_ashr_i32 s54, s70, 31
	s_mov_b32 s85, s91
	s_and_b32 s56, s84, 6
	v_lshl_or_b32 v241, s80, 5, v0
	v_lshl_add_u64 v[198:199], s[4:5], 0, v[6:7]
	v_add_u32_e32 v242, 0, v12
	v_lshlrev_b32_e32 v200, 1, v0
	v_lshlrev_b32_e32 v202, 1, v8
	s_barrier
	s_branch .LBB0_261

;     __device__ bool next(int i, Unit& u) const {
;         const long L = (long)i * G + c; if (L >= nwg) return false;
;         int wgid = (int)L; { const int q = nwg / NXCD, r = nwg % NXCD, xcd = wgid % NXCD, off = wgid / NXCD; wgid = (xcd < r ? xcd * (q + 1) : r * (q + 1) + (xcd - r) * q) + off; }
;         const int nig = WGM * nN, gid = wgid / nig, fm = gid * WGM, gsz = (nM - fm) < WGM ? (nM - fm) : WGM;
;         u.pm = fm + ((wgid % nig) % gsz); u.pn = (wgid % nig) / gsz; return true;
;     }
.LBB0_266:
	s_ashr_i32 s5, s5, 3
	s_add_i32 s5, s21, s5
	s_abs_i32 s19, s5
	s_mul_hi_u32 s20, s19, s55
	s_mul_i32 s21, s20, s57
	s_sub_i32 s19, s19, s21
	s_ashr_i32 s18, s5, 31
	s_add_i32 s21, s20, 1
	s_sub_i32 s22, s19, s57
	s_cmp_ge_u32 s19, s57
	s_cselect_b32 s20, s21, s20
	s_cselect_b32 s19, s22, s19
	s_add_i32 s21, s20, 1
	s_cmp_ge_u32 s19, s57
	s_cselect_b32 s19, s21, s20
	s_xor_b32 s19, s19, s18
	s_sub_i32 s18, s19, s18
	s_lshl_b32 s19, s18, 2
	s_sub_i32 s20, s96, s19
	s_min_i32 s20, s20, 4
	s_abs_i32 s21, s20
	v_cvt_f32_u32_e32 v0, s21
	s_sub_i32 s23, 0, s21
	s_mul_i32 s18, s18, s57
	s_sub_i32 s18, s5, s18
	v_rcp_iflag_f32_e32 v0, v0
	s_abs_i32 s5, s18
	s_xor_b32 s22, s18, s20
	s_ashr_i32 s22, s22, 31
	v_mul_f32_e32 v0, 0x4f7ffffe, v0
	v_cvt_u32_f32_e32 v0, v0
	s_nop 0
	v_readfirstlane_b32 s38, v0
	s_mul_i32 s23, s23, s38
	s_mul_hi_u32 s23, s38, s23
	s_add_i32 s38, s38, s23
	s_mul_hi_u32 s23, s5, s38
	s_mul_i32 s38, s23, s21
	s_sub_i32 s5, s5, s38
	s_add_i32 s38, s23, 1
	s_sub_i32 s39, s5, s21
	s_cmp_ge_u32 s5, s21
	s_cselect_b32 s23, s38, s23
	s_cselect_b32 s5, s39, s5
	s_add_i32 s38, s23, 1
	s_cmp_ge_u32 s5, s21
	s_cselect_b32 s5, s38, s23
	s_xor_b32 s5, s5, s22
	s_sub_i32 s5, s5, s22
	s_mul_i32 s20, s5, s20
	s_sub_i32 s18, s18, s20
	s_add_i32 s62, s18, s19
